# phase 1: half the workgroups run weight set-up before the norm pass (overlap HBM-bound and compute-bound halves); plus EpiAct epilogue
# speedup vs baseline: 1.0044x; 1.0044x over previous
.LBB0_66:
	s_mov_b32 s98, 0
	s_cmp_lt_i32 s24, 2
	s_cselect_b64 s[18:19], -1, 0
	s_and_b64 s[4:5], s[18:19], s[4:5]
	s_andn2_b64 vcc, exec, s[4:5]
	s_mul_i32 s61, s2, 0xc0
	s_mul_i32 s62, s3, 24
	s_cbranch_vccnz .LBB0_124
	s_bfe_u32 s98, s2, 0x10003
.Lp1_top:
	s_mov_b64 s[4:5], s[0:1]
	s_mov_b32 s6, 0
	s_and_b32 s7, s33, 0xffffffc0
	v_mbcnt_lo_u32_b32 v0, -1, s6
	v_mbcnt_hi_u32_b32 v0, -1, v0
	v_or_b32_e32 v103, s7, v0
	v_mbcnt_lo_u32_b32 v0, -1, 0
	v_mbcnt_hi_u32_b32 v0, -1, v0
	v_and_b32_e32 v1, 64, v0
	v_add_u32_e32 v1, 64, v1
	v_xor_b32_e32 v2, 1, v0
	v_cmp_lt_i32_e32 vcc, v2, v1
	v_mov_b32_e32 v97, 0
	v_and_b32_e32 v102, 63, v103
	v_cndmask_b32_e32 v2, v0, v2, vcc
	v_lshlrev_b32_e32 v109, 2, v2
	v_xor_b32_e32 v2, 2, v0
	v_cmp_lt_i32_e32 vcc, v2, v1
	v_lshlrev_b32_e32 v96, 3, v102
	s_load_dword s44, s[0:1], 0xb8
	s_load_dwordx2 s[38:39], s[4:5], 0xa0
	s_load_dwordx4 s[28:31], s[4:5], 0x0
	s_load_dwordx2 s[6:7], s[4:5], 0x20
	s_load_dwordx2 s[26:27], s[4:5], 0x70
	s_load_dwordx4 s[20:23], s[4:5], 0x60
	s_load_dwordx8 s[8:15], s[4:5], 0x40
	v_cndmask_b32_e32 v2, v0, v2, vcc
	v_lshlrev_b32_e32 v108, 2, v2
	v_xor_b32_e32 v2, 4, v0
	v_cmp_lt_i32_e32 vcc, v2, v1
	s_mov_b64 s[4:5], 0xe800000
	s_waitcnt lgkmcnt(0)
	s_add_u32 s45, s38, 0x100000
	v_cndmask_b32_e32 v2, v0, v2, vcc
	v_lshlrev_b32_e32 v107, 2, v2
	v_xor_b32_e32 v2, 8, v0
	v_cmp_lt_i32_e32 vcc, v2, v1
	s_mov_b32 s41, 0
	s_mov_b32 s51, -1
	v_cndmask_b32_e32 v2, v0, v2, vcc
	v_lshlrev_b32_e32 v106, 2, v2
	v_xor_b32_e32 v2, 16, v0
	v_cmp_lt_i32_e32 vcc, v2, v1
	s_addc_u32 s46, s39, 0
	s_add_i32 s47, s61, s62
	v_cndmask_b32_e32 v2, v0, v2, vcc
	v_lshlrev_b32_e32 v105, 2, v2
	v_xor_b32_e32 v2, 32, v0
	v_cmp_lt_i32_e32 vcc, v2, v1
	v_mov_b32_e32 v110, 0x358637bd
	s_mov_b32 s48, 0xf800000
	v_cndmask_b32_e32 v0, v0, v2, vcc
	v_lshlrev_b32_e32 v104, 2, v0
	v_lshl_add_u64 v[0:1], s[38:39], 0, v[96:97]
	v_lshl_add_u64 v[98:99], v[0:1], 0, s[4:5]
	v_lshlrev_b32_e32 v0, 5, v102
	v_mov_b32_e32 v1, v97
	v_lshl_add_u64 v[100:101], s[6:7], 0, v[0:1]
	v_or_b32_e32 v0, 0x200, v96
	v_lshlrev_b32_e32 v97, 2, v0
	v_mov_b32_e32 v111, 0x260
	s_mov_b32 s49, 0xc3e00000
	v_lshlrev_b32_e32 v112, 2, v96
	v_mov_b32_e32 v113, 0x43e00000
	s_mov_b32 s50, 0
	s_cmp_eq_u32 s98, 1
	s_cbranch_scc1 .LBB0_75
	s_branch .LBB0_69

.LBB0_75:
	s_cmp_eq_u32 s98, 2
	s_cbranch_scc1 .LBB0_124
	s_bfe_u32 s5, s2, 0x20002
	s_lshl_b32 s4, s2, 2
	s_andn2_b32 s4, s4, 63
	s_lshl_b32 s28, s5, 10
	s_add_u32 s6, s22, s28
	v_lshlrev_b32_e32 v0, 2, v103
	v_add_u32_e32 v4, 0xe00, v103
	v_add_u32_e32 v6, 0xc00, v103
	v_add_u32_e32 v8, 0xa00, v103
	v_add_u32_e32 v10, 0x800, v103
	v_add_u32_e32 v12, 0x600, v103
	v_add_u32_e32 v14, 0x400, v103
	v_add_u32_e32 v16, 0x200, v103
	s_addc_u32 s7, s23, 0
	v_and_b32_e32 v2, 0x3fc, v0
	v_mov_b32_e32 v3, 0
	v_lshrrev_b32_e32 v4, 8, v4
	v_lshrrev_b32_e32 v6, 8, v6
	v_lshrrev_b32_e32 v8, 8, v8
	v_lshrrev_b32_e32 v10, 8, v10
	v_lshrrev_b32_e32 v12, 8, v12
	v_lshrrev_b32_e32 v14, 8, v14
	v_lshrrev_b32_e32 v16, 8, v16
	v_lshrrev_b32_e32 v18, 8, v103
	s_mov_b32 s29, 0
	v_lshl_add_u64 v[0:1], s[6:7], 0, v[2:3]
	v_add_u32_e32 v2, 0, v2
	v_add_u32_e32 v3, 0xfffff000, v103
	v_add_u32_e32 v5, s4, v4
	v_add_u32_e32 v7, s4, v6
	v_add_u32_e32 v9, s4, v8
	v_add_u32_e32 v11, s4, v10
	v_add_u32_e32 v13, s4, v12
	v_add_u32_e32 v15, s4, v14
	v_add_u32_e32 v17, s4, v16
	v_add_u32_e32 v19, s4, v18
	s_mov_b64 s[6:7], 0
	s_movk_i32 s22, 0x404
	s_movk_i32 s23, 0x2fff

.LBB0_124:
	s_cmp_eq_u32 s98, 1
	s_cbranch_scc0 .Lp1_done
	s_mov_b32 s98, 2
	s_branch .Lp1_top
